# phase 0 transposes only wt_gla_in; other weight-image tiles done by idle workgroups at the end of phase 1 (wg>=64) and phase 3 (wg>=128)
# speedup vs baseline: 1.0195x; 1.0195x over previous
.LBB0_17:
	s_load_dwordx16 s[4:19], s[0:1], 0x40
	s_cmp_lt_i32 s24, 1
	s_waitcnt lgkmcnt(0)
	v_writelane_b32 v230, s4, 0
	s_nop 1
	v_writelane_b32 v230, s5, 1
	v_writelane_b32 v230, s6, 2
	v_writelane_b32 v230, s7, 3
	v_writelane_b32 v230, s8, 4
	v_writelane_b32 v230, s9, 5
	v_writelane_b32 v230, s10, 6
	v_writelane_b32 v230, s11, 7
	v_writelane_b32 v230, s12, 8
	v_writelane_b32 v230, s13, 9
	v_writelane_b32 v230, s14, 10
	v_writelane_b32 v230, s15, 11
	v_writelane_b32 v230, s16, 12
	v_writelane_b32 v230, s17, 13
	v_writelane_b32 v230, s18, 14
	v_writelane_b32 v230, s19, 15
	s_cselect_b64 s[4:5], -1, 0
	s_cmp_gt_i32 s25, 0
	s_cselect_b64 s[6:7], -1, 0
	s_and_b64 s[4:5], s[4:5], s[6:7]
	s_andn2_b64 vcc, exec, s[4:5]
	s_cbranch_vccnz .LBB0_147
	s_lshl_b32 s3, s2, 1
	s_cmpk_gt_i32 s3, 0x33f
	s_cbranch_scc1 .LBB0_75
	v_lshlrev_b32_e32 v0, 3, v129
	s_load_dword s4, s[0:1], 0x148
	v_lshrrev_b32_e32 v14, 8, v129
	v_and_b32_e32 v0, 56, v0
	v_bfe_u32 v18, v129, 3, 5
	v_lshl_add_u32 v2, v14, 15, 0
	v_and_b32_e32 v15, 63, v129
	v_and_b32_e32 v3, 16, v129
	v_mul_u32_u24_e32 v5, 0x104, v0
	v_lshlrev_b32_e32 v6, 2, v18
	v_bfe_u32 v16, v129, 6, 2
	v_lshl_add_u32 v4, v15, 2, v2
	v_add3_u32 v19, v2, v5, v6
	v_mov_b32_e32 v2, s57
	v_mov_b32_e32 v6, s55
	v_cmp_eq_u32_e32 vcc, 0, v3
	v_mul_u32_u24_e32 v5, 0x104, v16
	v_and_b32_e32 v17, 15, v129
	v_cndmask_b32_e32 v3, v2, v6, vcc
	v_mov_b32_e32 v2, s56
	v_mov_b32_e32 v6, s54
	v_mov_b32_e32 v1, 0
	s_waitcnt lgkmcnt(0)
	s_lshl_b32 s16, s4, 1
	v_or_b32_e32 v20, 32, v18
	v_cndmask_b32_e32 v2, v2, v6, vcc
	v_add_u32_e32 v21, v4, v5
	v_lshlrev_b32_e32 v0, 1, v0
	s_branch .LBB0_21
.LBB0_20:
	s_or_b64 exec, exec, s[4:5]
	s_waitcnt vmcnt(0)
	ds_write_b32 v21, v12
	ds_write_b32 v21, v11 offset:1040
	ds_write_b32 v21, v26 offset:2080
	ds_write_b32 v21, v25 offset:3120
	ds_write_b32 v21, v28 offset:4160
	ds_write_b32 v21, v27 offset:5200
	ds_write_b32 v21, v30 offset:6240
	ds_write_b32 v21, v29 offset:7280
	ds_write_b32 v21, v32 offset:8320
	ds_write_b32 v21, v31 offset:9360
	ds_write_b32 v21, v34 offset:10400
	ds_write_b32 v21, v33 offset:11440
	ds_write_b32 v21, v36 offset:12480
	ds_write_b32 v21, v35 offset:13520
	ds_write_b32 v21, v38 offset:14560
	ds_write_b32 v21, v37 offset:15600
	v_ashrrev_i32_e32 v11, 31, v10
	s_waitcnt lgkmcnt(0)
	s_barrier
	v_lshl_add_u64 v[4:5], v[10:11], 1, v[4:5]
	ds_read2_b32 v[8:9], v19 offset1:32
	ds_read2_b32 v[10:11], v19 offset0:65 offset1:97
	ds_read2_b32 v[12:13], v19 offset0:130 offset1:162
	ds_read2_b32 v[24:25], v19 offset0:195 offset1:227
	v_add_u32_e32 v6, 0x400, v19
	ds_read2_b32 v[26:27], v6 offset0:4 offset1:36
	ds_read2_b32 v[28:29], v6 offset0:69 offset1:101
	ds_read2_b32 v[30:31], v6 offset0:134 offset1:166
	ds_read2_b32 v[32:33], v6 offset0:199 offset1:231
	v_lshl_add_u64 v[34:35], v[4:5], 0, v[0:1]
	s_waitcnt lgkmcnt(6)
	v_cvt_pk_bf16_f32 v4, v8, v10
	v_or_b32_e32 v8, v23, v18
	v_ashrrev_i32_e32 v10, 31, v23
	v_mul_lo_u32 v10, v10, v22
	v_mad_u64_u32 v[36:37], s[4:5], v8, v22, 0
	v_add_u32_e32 v37, v37, v10
	s_waitcnt lgkmcnt(4)
	v_cvt_pk_bf16_f32 v5, v12, v24
	s_waitcnt lgkmcnt(2)
	v_cvt_pk_bf16_f32 v6, v26, v28
	s_waitcnt lgkmcnt(0)
	v_cvt_pk_bf16_f32 v7, v30, v32
	v_lshl_add_u64 v[36:37], v[36:37], 1, v[34:35]
	v_or_b32_e32 v8, v23, v20
	global_store_dwordx4 v[36:37], v[4:7], off
	s_add_i32 s3, s3, s16
	s_cmpk_lt_i32 s3, 0x340
	v_cvt_pk_bf16_f32 v4, v9, v11
	v_mad_u64_u32 v[8:9], s[4:5], v8, v22, 0
	v_add_u32_e32 v9, v9, v10
	v_cvt_pk_bf16_f32 v5, v13, v25
	v_cvt_pk_bf16_f32 v6, v27, v29
	v_cvt_pk_bf16_f32 v7, v31, v33
	v_lshl_add_u64 v[8:9], v[8:9], 1, v[34:35]
	global_store_dwordx4 v[8:9], v[4:7], off
	s_cbranch_scc0 .LBB0_75

.LBB0_165:
	s_cmp_lt_u32 s2, 64
	s_cbranch_scc1 .Ltr1_skip
	s_sub_u32 s3, s2, 64
	s_lshl_b32 s3, s3, 1
	s_addk_i32 s3, 0x340
	s_cmpk_gt_i32 s3, 0xf3f
	s_cbranch_scc1 .Ltr1_75
	s_load_dwordx4 s[84:87], s[0:1], 0x100
	s_load_dwordx4 s[88:91], s[0:1], 0xc8
	s_waitcnt lgkmcnt(0)
	s_barrier
	v_lshlrev_b32_e32 v0, 3, v129
	v_lshrrev_b32_e32 v14, 8, v129
	v_and_b32_e32 v0, 56, v0
	v_bfe_u32 v18, v129, 3, 5
	v_lshl_add_u32 v2, v14, 15, 0
	v_and_b32_e32 v15, 63, v129
	v_and_b32_e32 v3, 16, v129
	v_mul_u32_u24_e32 v5, 0x104, v0
	v_lshlrev_b32_e32 v6, 2, v18
	v_bfe_u32 v16, v129, 6, 2
	v_lshl_add_u32 v4, v15, 2, v2
	v_add3_u32 v19, v2, v5, v6
	v_mov_b32_e32 v2, s91
	v_mov_b32_e32 v6, s89
	v_cmp_eq_u32_e32 vcc, 0, v3
	v_mul_u32_u24_e32 v5, 0x104, v16
	v_and_b32_e32 v17, 15, v129
	v_cndmask_b32_e32 v3, v2, v6, vcc
	v_mov_b32_e32 v2, s90
	v_mov_b32_e32 v6, s88
	v_mov_b32_e32 v1, 0
	s_waitcnt lgkmcnt(0)
	s_movk_i32 s16, 0x180
	v_or_b32_e32 v20, 32, v18
	v_cndmask_b32_e32 v2, v2, v6, vcc
	v_add_u32_e32 v21, v4, v5
	v_lshlrev_b32_e32 v0, 1, v0
	s_branch .Ltr1_21
.Ltr1_20:
	s_or_b64 exec, exec, s[4:5]
	s_waitcnt vmcnt(0)
	ds_write_b32 v21, v12
	ds_write_b32 v21, v11 offset:1040
	ds_write_b32 v21, v26 offset:2080
	ds_write_b32 v21, v25 offset:3120
	ds_write_b32 v21, v28 offset:4160
	ds_write_b32 v21, v27 offset:5200
	ds_write_b32 v21, v30 offset:6240
	ds_write_b32 v21, v29 offset:7280
	ds_write_b32 v21, v32 offset:8320
	ds_write_b32 v21, v31 offset:9360
	ds_write_b32 v21, v34 offset:10400
	ds_write_b32 v21, v33 offset:11440
	ds_write_b32 v21, v36 offset:12480
	ds_write_b32 v21, v35 offset:13520
	ds_write_b32 v21, v38 offset:14560
	ds_write_b32 v21, v37 offset:15600
	v_ashrrev_i32_e32 v11, 31, v10
	s_waitcnt lgkmcnt(0)
	s_barrier
	v_lshl_add_u64 v[4:5], v[10:11], 1, v[4:5]
	ds_read2_b32 v[8:9], v19 offset1:32
	ds_read2_b32 v[10:11], v19 offset0:65 offset1:97
	ds_read2_b32 v[12:13], v19 offset0:130 offset1:162
	ds_read2_b32 v[24:25], v19 offset0:195 offset1:227
	v_add_u32_e32 v6, 0x400, v19
	ds_read2_b32 v[26:27], v6 offset0:4 offset1:36
	ds_read2_b32 v[28:29], v6 offset0:69 offset1:101
	ds_read2_b32 v[30:31], v6 offset0:134 offset1:166
	ds_read2_b32 v[32:33], v6 offset0:199 offset1:231
	v_lshl_add_u64 v[34:35], v[4:5], 0, v[0:1]
	s_waitcnt lgkmcnt(6)
	v_cvt_pk_bf16_f32 v4, v8, v10
	v_or_b32_e32 v8, v23, v18
	v_ashrrev_i32_e32 v10, 31, v23
	v_mul_lo_u32 v10, v10, v22
	v_mad_u64_u32 v[36:37], s[4:5], v8, v22, 0
	v_add_u32_e32 v37, v37, v10
	s_waitcnt lgkmcnt(4)
	v_cvt_pk_bf16_f32 v5, v12, v24
	s_waitcnt lgkmcnt(2)
	v_cvt_pk_bf16_f32 v6, v26, v28
	s_waitcnt lgkmcnt(0)
	v_cvt_pk_bf16_f32 v7, v30, v32
	v_lshl_add_u64 v[36:37], v[36:37], 1, v[34:35]
	v_or_b32_e32 v8, v23, v20
	global_store_dwordx4 v[36:37], v[4:7], off
	s_add_i32 s3, s3, s16
	s_cmpk_lt_i32 s3, 0xf40
	v_cvt_pk_bf16_f32 v4, v9, v11
	v_mad_u64_u32 v[8:9], s[4:5], v8, v22, 0
	v_add_u32_e32 v9, v9, v10
	v_cvt_pk_bf16_f32 v5, v13, v25
	v_cvt_pk_bf16_f32 v6, v27, v29
	v_cvt_pk_bf16_f32 v7, v31, v33
	v_lshl_add_u64 v[8:9], v[8:9], 1, v[34:35]
	global_store_dwordx4 v[8:9], v[4:7], off
	s_cbranch_scc0 .Ltr1_75
.Ltr1_21:
	s_load_dwordx16 s[68:83], s[0:1], 0x40
	v_add_u32_e32 v24, s3, v14
	s_movk_i32 s4, 0x33f
	v_cmp_lt_i32_e32 vcc, s4, v24
	v_mov_b64_e32 v[6:7], 0xc10
	v_mov_b32_e32 v22, 0x400
	v_mov_b32_e32 v25, 0xc10
	v_mov_b64_e32 v[4:5], s[60:61]
	s_waitcnt lgkmcnt(0)
	v_mov_b64_e32 v[10:11], s[74:75]
	s_mov_b64 s[6:7], -1
	s_and_saveexec_b64 s[4:5], vcc
	s_cbranch_execz .Ltr1_39
	s_load_dwordx16 s[68:83], s[0:1], 0x40
	s_movk_i32 s6, 0x43f
	v_cmp_lt_u32_e32 vcc, s6, v24
	v_mov_b64_e32 v[4:5], s[62:63]
	s_waitcnt lgkmcnt(0)
	v_mov_b64_e32 v[10:11], s[82:83]
	s_and_saveexec_b64 s[8:9], vcc
	s_xor_b64 s[8:9], exec, s[8:9]
	s_cbranch_execz .Ltr1_36
	s_movk_i32 s6, 0xc3f
	v_cmp_lt_u32_e32 vcc, s6, v24
	s_and_saveexec_b64 s[10:11], vcc
	s_xor_b64 s[10:11], exec, s[10:11]
	s_cbranch_execz .Ltr1_33
	s_movk_i32 s6, 0x143f
	v_cmp_lt_u32_e32 vcc, s6, v24
	s_and_saveexec_b64 s[12:13], vcc
	s_xor_b64 s[12:13], exec, s[12:13]
	s_cbranch_execz .Ltr1_30
	s_load_dwordx16 s[68:83], s[0:1], 0x80
	s_movk_i32 s6, 0x153f
	v_cmp_lt_u32_e32 vcc, s6, v24
	v_mov_b64_e32 v[4:5], s[84:85]
	s_waitcnt lgkmcnt(0)
	v_mov_b64_e32 v[10:11], s[68:69]
	s_and_saveexec_b64 s[6:7], vcc
	s_xor_b64 s[6:7], exec, s[6:7]
	v_add_u32_e32 v24, 0xffffeac0, v24
	v_mov_b64_e32 v[10:11], s[88:89]
	v_mov_b64_e32 v[4:5], s[86:87]
	s_or_saveexec_b64 s[14:15], s[6:7]
	s_mov_b64 s[6:7], 0
	v_mov_b32_e32 v25, 0x800
	s_xor_b64 exec, exec, s[14:15]
	s_mov_b64 s[6:7], exec
	v_add_u32_e32 v24, 0xffffebc0, v24
	v_mov_b32_e32 v25, 0x400
	s_or_b64 exec, exec, s[14:15]

.Ltr1_75:
	s_load_dword s3, s[0:1], 0x148
	s_add_u32 s6, s0, 0x148
	s_addc_u32 s7, s1, 0
	s_waitcnt lgkmcnt(0)

.LBB0_362:
	s_cmp_lt_u32 s2, 128
	s_cbranch_scc1 .Ltr2_skip
	s_sub_u32 s3, s2, 128
	s_lshl_b32 s3, s3, 1
	s_addk_i32 s3, 0xf40
	s_cmpk_gt_i32 s3, 0x173f
	s_cbranch_scc1 .Ltr2_75
	s_load_dwordx4 s[84:87], s[0:1], 0x100
	s_load_dwordx4 s[88:91], s[0:1], 0xc8
	s_waitcnt lgkmcnt(0)
	s_barrier
	v_lshlrev_b32_e32 v0, 3, v129
	v_lshrrev_b32_e32 v14, 8, v129
	v_and_b32_e32 v0, 56, v0
	v_bfe_u32 v18, v129, 3, 5
	v_lshl_add_u32 v2, v14, 15, 0
	v_and_b32_e32 v15, 63, v129
	v_and_b32_e32 v3, 16, v129
	v_mul_u32_u24_e32 v5, 0x104, v0
	v_lshlrev_b32_e32 v6, 2, v18
	v_bfe_u32 v16, v129, 6, 2
	v_lshl_add_u32 v4, v15, 2, v2
	v_add3_u32 v19, v2, v5, v6
	v_mov_b32_e32 v2, s91
	v_mov_b32_e32 v6, s89
	v_cmp_eq_u32_e32 vcc, 0, v3
	v_mul_u32_u24_e32 v5, 0x104, v16
	v_and_b32_e32 v17, 15, v129
	v_cndmask_b32_e32 v3, v2, v6, vcc
	v_mov_b32_e32 v2, s90
	v_mov_b32_e32 v6, s88
	v_mov_b32_e32 v1, 0
	s_waitcnt lgkmcnt(0)
	s_movk_i32 s16, 0x100
	v_or_b32_e32 v20, 32, v18
	v_cndmask_b32_e32 v2, v2, v6, vcc
	v_add_u32_e32 v21, v4, v5
	v_lshlrev_b32_e32 v0, 1, v0
	s_branch .Ltr2_21

.Ltr2_75:
	s_load_dword s3, s[0:1], 0x148
	s_add_u32 s26, s0, 0x148
	s_addc_u32 s27, s1, 0
	s_waitcnt lgkmcnt(0)
